# FF1 and FF2 K-loops: LDS-DMA loads addressed as SGPR base + 32-bit lane offset (no per-load v_lshl_add_u64, half the address-VGPR traffic)
# baseline (speedup 1.0000x reference)
; #define PG8_STAGE(bufoff, gbase, voff) do { _Pragma("unroll") for (int _i = 0; _i < 2; ++_i) \
;         __builtin_amdgcn_global_load_lds((const unsigned*)((const char*)(gbase) + (voff)[_i]), (PG8_LAS unsigned*)(lds + (bufoff) + ldsw + _i * 8192), 16, 0, 0); } while (0)
; #define PG8_LDA(dst, b, h) do { _Pragma("unroll") for (int m = 0; m < 4; ++m) _Pragma("unroll") for (int k = 0; k < 2; ++k) dst[m][k] = *(const PG8_LAS bf16x8*)(lds + PG8_SA(b, h) + aoff + m * 2048 + k * 1024); } while (0)
; #define PG8_LDB(dst, b, h) do { _Pragma("unroll") for (int n = 0; n < 2; ++n) _Pragma("unroll") for (int k = 0; k < 2; ++k) dst[n][k] = *(const PG8_LAS bf16x8*)(lds + PG8_SB(b, h) + boff + n * 2048 + k * 1024); } while (0)
; #define PG8_MMA(ai, bj, At, Bt) do { __builtin_amdgcn_s_setprio(1); _Pragma("unroll") for (int m = 0; m < 4; ++m) _Pragma("unroll") for (int n = 0; n < 2; ++n) _Pragma("unroll") for (int k = 0; k < 2; ++k) \
;         acc[ai][bj][m][n] = __builtin_amdgcn_mfma_f32_16x16x32_bf16(Bt[n][k], At[m][k], acc[ai][bj][m][n], 0, 0, 0); __builtin_amdgcn_s_setprio(0); } while (0)
; #define PG8_WAIT_V(n) asm volatile("s_waitcnt vmcnt(" #n ")" ::: "memory")
; #define PG8_BAR __builtin_amdgcn_s_barrier()
; template <class Epi, class Sched, bool ALIGN_EPI = false, bool SP2 = false>
; __device__ __forceinline__ void gemm_phase(PG8_LAS unsigned char* lds, const Gemm g, const Sched& S, const Epi& E) {
;     ...
;         for (int t = 0; t < nt; t += 2) {
;             const bool last = (t == nt - 2);
;             const char* a1 = cA + (size_t)(t + 1) * kstep;
;             const char* a2 = last ? nA : cA + (size_t)(t + 2) * kstep; const char* b2 = last ? nB : cB + (size_t)(t + 2) * kstep;
;             const char* a3 = a2 + kstep; const char* b3 = b2 + kstep;
;             if (last && has_next) S.a_ready(nxt);
;             if constexpr (SP2) {
;             PG8_LDB(B0, 0, 0); PG8_LDB(B1, 0, 1); PG8_SCHED; PG8_LDA(At, 0, 0); PG8_STAGE(PG8_SA(1, 1), a1 + hstepA, voffA);
;             PG8_WAIT_V(8); PG8_WAIT_L(0); PG8_BAR; PG8_MMA(0, 0, At, B0); PG8_MMA(0, 1, At, B1); PG8_BAR; PG8_SCHED;
;             PG8_LDA(At, 0, 1); PG8_STAGE(PG8_SB(0, 0), b2, voffB); PG8_STAGE(PG8_SB(0, 1), b2 + hstepB, voffB); PG8_STAGE(PG8_SA(0, 0), a2, voffA);
;             PG8_WAIT_V(8); PG8_WAIT_L(0); PG8_BAR; PG8_MMA(1, 0, At, B0); PG8_MMA(1, 1, At, B1); PG8_BAR; PG8_SCHED;
.LBB0_1061:
	ds_read_b128 v[128:131], v199
	ds_read_b128 v[132:135], v199 offset:1024
	ds_read_b128 v[136:139], v199 offset:2048
	ds_read_b128 v[140:143], v199 offset:3072
	ds_read_b128 v[144:147], v200
	ds_read_b128 v[148:151], v200 offset:1024
	ds_read_b128 v[152:155], v200 offset:2048
	ds_read_b128 v[156:159], v200 offset:3072
	s_add_u32 s20, s18, 0xfff00080
	s_addc_u32 s21, s19, -1
	s_cmp_eq_u32 s45, 60
	s_cselect_b32 s23, s11, s21
	s_cselect_b32 s22, s41, s20
	s_cselect_b32 s21, s9, s44
	s_cselect_b32 s20, s42, s43
	s_add_i32 m0, s17, 0xc000
	ds_read_b128 v[160:163], v201
	ds_read_b128 v[164:167], v201 offset:1024
	ds_read_b128 v[188:191], v201 offset:2048
	ds_read_b128 v[192:195], v201 offset:3072
	ds_read_b128 v[202:205], v201 offset:4096
	ds_read_b128 v[206:209], v201 offset:5120
	ds_read_b128 v[210:213], v201 offset:6144
	ds_read_b128 v[214:217], v201 offset:7168
	global_load_lds_dwordx4 v180, s[18:19]
	s_add_i32 m0, s17, 0xe000
	s_nop 0
	global_load_lds_dwordx4 v182, s[18:19]
	s_waitcnt vmcnt(8)
	s_waitcnt lgkmcnt(0)
	s_barrier
	s_setprio 1
	s_waitcnt lgkmcnt(0)
	v_mfma_f32_16x16x32_bf16 v[124:127], v[128:131], v[160:163], v[124:127]
	v_mfma_f32_16x16x32_bf16 v[120:123], v[136:139], v[160:163], v[120:123]
	v_mfma_f32_16x16x32_bf16 v[112:115], v[128:131], v[188:191], v[112:115]
	v_mfma_f32_16x16x32_bf16 v[104:107], v[136:139], v[188:191], v[104:107]
	v_mfma_f32_16x16x32_bf16 v[96:99], v[128:131], v[202:205], v[96:99]
	v_mfma_f32_16x16x32_bf16 v[88:91], v[136:139], v[202:205], v[88:91]
	v_mfma_f32_16x16x32_bf16 v[80:83], v[128:131], v[210:213], v[80:83]
	v_mfma_f32_16x16x32_bf16 v[72:75], v[136:139], v[210:213], v[72:75]
	v_mfma_f32_16x16x32_bf16 v[124:127], v[132:135], v[164:167], v[124:127]
	v_mfma_f32_16x16x32_bf16 v[120:123], v[140:143], v[164:167], v[120:123]
	v_mfma_f32_16x16x32_bf16 v[112:115], v[132:135], v[192:195], v[112:115]
	v_mfma_f32_16x16x32_bf16 v[104:107], v[140:143], v[192:195], v[104:107]
	v_mfma_f32_16x16x32_bf16 v[96:99], v[132:135], v[206:209], v[96:99]
	v_mfma_f32_16x16x32_bf16 v[88:91], v[140:143], v[206:209], v[88:91]
	v_mfma_f32_16x16x32_bf16 v[80:83], v[132:135], v[214:217], v[80:83]
	v_mfma_f32_16x16x32_bf16 v[72:75], v[140:143], v[214:217], v[72:75]
	v_mfma_f32_16x16x32_bf16 v[116:119], v[144:147], v[160:163], v[116:119]
	v_mfma_f32_16x16x32_bf16 v[108:111], v[152:155], v[160:163], v[108:111]
	v_mfma_f32_16x16x32_bf16 v[100:103], v[144:147], v[188:191], v[100:103]
	v_mfma_f32_16x16x32_bf16 v[92:95], v[152:155], v[188:191], v[92:95]
	v_mfma_f32_16x16x32_bf16 v[84:87], v[144:147], v[202:205], v[84:87]
	v_mfma_f32_16x16x32_bf16 v[76:79], v[152:155], v[202:205], v[76:79]
	v_mfma_f32_16x16x32_bf16 v[68:71], v[144:147], v[210:213], v[68:71]
	v_mfma_f32_16x16x32_bf16 v[64:67], v[152:155], v[210:213], v[64:67]
	v_mfma_f32_16x16x32_bf16 v[116:119], v[148:151], v[164:167], v[116:119]
	v_mfma_f32_16x16x32_bf16 v[108:111], v[156:159], v[164:167], v[108:111]
	v_mfma_f32_16x16x32_bf16 v[100:103], v[148:151], v[192:195], v[100:103]
	v_mfma_f32_16x16x32_bf16 v[92:95], v[156:159], v[192:195], v[92:95]
	v_mfma_f32_16x16x32_bf16 v[84:87], v[148:151], v[206:209], v[84:87]
	v_mfma_f32_16x16x32_bf16 v[76:79], v[156:159], v[206:209], v[76:79]
	v_mfma_f32_16x16x32_bf16 v[68:71], v[148:151], v[214:217], v[68:71]
	v_mfma_f32_16x16x32_bf16 v[64:67], v[156:159], v[214:217], v[64:67]
	s_setprio 0
	s_barrier
	s_add_i32 s46, s38, s29
	s_mov_b32 m0, s46
	ds_read_b128 v[160:163], v201 offset:16384
	ds_read_b128 v[164:167], v201 offset:17408
	ds_read_b128 v[188:191], v201 offset:18432
	ds_read_b128 v[192:195], v201 offset:19456
	ds_read_b128 v[202:205], v201 offset:20480
	ds_read_b128 v[206:209], v201 offset:21504
	ds_read_b128 v[210:213], v201 offset:22528
	ds_read_b128 v[214:217], v201 offset:23552
	global_load_lds_dwordx4 v170, s[20:21]
	s_add_i32 m0, s46, 0x2000
	s_add_u32 s46, s20, 0x100000
	s_addc_u32 s47, s21, 0
	s_add_u32 s80, s22, s4
	s_addc_u32 s81, s23, s5
	s_add_i32 s48, s39, s29
	global_load_lds_dwordx4 v174, s[20:21]
	s_mov_b32 m0, s48
	s_nop 0
	global_load_lds_dwordx4 v170, s[46:47]
	s_add_i32 m0, s48, 0x2000
	s_nop 0
	global_load_lds_dwordx4 v174, s[46:47]
	s_mov_b32 m0, s17
	s_nop 0
	global_load_lds_dwordx4 v168, s[22:23]
	s_mov_b32 m0, s30
	s_nop 0
	global_load_lds_dwordx4 v172, s[22:23]
	s_waitcnt vmcnt(8)
	s_waitcnt lgkmcnt(0)
	s_barrier
	s_setprio 1
	s_waitcnt lgkmcnt(0)
	v_mfma_f32_16x16x32_bf16 v[60:63], v[128:131], v[160:163], v[60:63]
	v_mfma_f32_16x16x32_bf16 v[56:59], v[136:139], v[160:163], v[56:59]
	v_mfma_f32_16x16x32_bf16 v[48:51], v[128:131], v[188:191], v[48:51]
	v_mfma_f32_16x16x32_bf16 v[40:43], v[136:139], v[188:191], v[40:43]
	v_mfma_f32_16x16x32_bf16 v[32:35], v[128:131], v[202:205], v[32:35]
	v_mfma_f32_16x16x32_bf16 v[24:27], v[136:139], v[202:205], v[24:27]
	v_mfma_f32_16x16x32_bf16 v[16:19], v[128:131], v[210:213], v[16:19]
	v_mfma_f32_16x16x32_bf16 v[8:11], v[136:139], v[210:213], v[8:11]
	v_mfma_f32_16x16x32_bf16 v[60:63], v[132:135], v[164:167], v[60:63]
	v_mfma_f32_16x16x32_bf16 v[56:59], v[140:143], v[164:167], v[56:59]
	v_mfma_f32_16x16x32_bf16 v[48:51], v[132:135], v[192:195], v[48:51]
	v_mfma_f32_16x16x32_bf16 v[40:43], v[140:143], v[192:195], v[40:43]
	v_mfma_f32_16x16x32_bf16 v[32:35], v[132:135], v[206:209], v[32:35]
	v_mfma_f32_16x16x32_bf16 v[24:27], v[140:143], v[206:209], v[24:27]
	v_mfma_f32_16x16x32_bf16 v[16:19], v[132:135], v[214:217], v[16:19]
	v_mfma_f32_16x16x32_bf16 v[8:11], v[140:143], v[214:217], v[8:11]
	v_mfma_f32_16x16x32_bf16 v[52:55], v[144:147], v[160:163], v[52:55]
	v_mfma_f32_16x16x32_bf16 v[44:47], v[152:155], v[160:163], v[44:47]
	v_mfma_f32_16x16x32_bf16 v[36:39], v[144:147], v[188:191], v[36:39]
	v_mfma_f32_16x16x32_bf16 v[28:31], v[152:155], v[188:191], v[28:31]
	v_mfma_f32_16x16x32_bf16 v[20:23], v[144:147], v[202:205], v[20:23]
	v_mfma_f32_16x16x32_bf16 v[12:15], v[152:155], v[202:205], v[12:15]
	v_mfma_f32_16x16x32_bf16 v[4:7], v[144:147], v[210:213], v[4:7]
	v_mfma_f32_16x16x32_bf16 v[0:3], v[152:155], v[210:213], v[0:3]
	v_mfma_f32_16x16x32_bf16 v[52:55], v[148:151], v[164:167], v[52:55]
	v_mfma_f32_16x16x32_bf16 v[44:47], v[156:159], v[164:167], v[44:47]
	v_mfma_f32_16x16x32_bf16 v[36:39], v[148:151], v[192:195], v[36:39]
	v_mfma_f32_16x16x32_bf16 v[28:31], v[156:159], v[192:195], v[28:31]
	v_mfma_f32_16x16x32_bf16 v[20:23], v[148:151], v[206:209], v[20:23]
	v_mfma_f32_16x16x32_bf16 v[12:15], v[156:159], v[206:209], v[12:15]
	v_mfma_f32_16x16x32_bf16 v[4:7], v[148:151], v[214:217], v[4:7]
	v_mfma_f32_16x16x32_bf16 v[0:3], v[156:159], v[214:217], v[0:3]
	s_setprio 0
	s_barrier
; #define PG8_STAGE(bufoff, gbase, voff) do { _Pragma("unroll") for (int _i = 0; _i < 2; ++_i) \
;         __builtin_amdgcn_global_load_lds((const unsigned*)((const char*)(gbase) + (voff)[_i]), (PG8_LAS unsigned*)(lds + (bufoff) + ldsw + _i * 8192), 16, 0, 0); } while (0)
; #define PG8_LDA(dst, b, h) do { _Pragma("unroll") for (int m = 0; m < 4; ++m) _Pragma("unroll") for (int k = 0; k < 2; ++k) dst[m][k] = *(const PG8_LAS bf16x8*)(lds + PG8_SA(b, h) + aoff + m * 2048 + k * 1024); } while (0)
; #define PG8_LDB(dst, b, h) do { _Pragma("unroll") for (int n = 0; n < 2; ++n) _Pragma("unroll") for (int k = 0; k < 2; ++k) dst[n][k] = *(const PG8_LAS bf16x8*)(lds + PG8_SB(b, h) + boff + n * 2048 + k * 1024); } while (0)
; #define PG8_MMA(ai, bj, At, Bt) do { __builtin_amdgcn_s_setprio(1); _Pragma("unroll") for (int m = 0; m < 4; ++m) _Pragma("unroll") for (int n = 0; n < 2; ++n) _Pragma("unroll") for (int k = 0; k < 2; ++k) \
;         acc[ai][bj][m][n] = __builtin_amdgcn_mfma_f32_16x16x32_bf16(Bt[n][k], At[m][k], acc[ai][bj][m][n], 0, 0, 0); __builtin_amdgcn_s_setprio(0); } while (0)
; #define PG8_WAIT_V(n) asm volatile("s_waitcnt vmcnt(" #n ")" ::: "memory")
; #define PG8_WAIT_L(n) asm volatile("s_waitcnt lgkmcnt(" #n ")" ::: "memory")
; #define PG8_BAR __builtin_amdgcn_s_barrier()
; #define PG8_SCHED __builtin_amdgcn_sched_barrier(0)
; template <class Epi, class Sched, bool ALIGN_EPI = false, bool SP2 = false>
; __device__ __forceinline__ void gemm_phase(PG8_LAS unsigned char* lds, const Gemm g, const Sched& S, const Epi& E) {
;     ...
;             PG8_LDB(B0, 1, 0); PG8_LDB(B1, 1, 1); PG8_SCHED; PG8_LDA(At, 1, 0); PG8_STAGE(PG8_SA(0, 1), a2 + hstepA, voffA);
;             PG8_WAIT_V(8); PG8_WAIT_L(0); PG8_BAR; PG8_MMA(0, 0, At, B0); PG8_MMA(0, 1, At, B1); PG8_BAR; PG8_SCHED;
;             PG8_LDA(At, 1, 1); PG8_STAGE(PG8_SB(1, 0), b3, voffB); PG8_STAGE(PG8_SB(1, 1), b3 + hstepB, voffB); PG8_STAGE(PG8_SA(1, 0), a3, voffA);
;             PG8_WAIT_V(8); PG8_WAIT_L(0); PG8_BAR; PG8_MMA(1, 0, At, B0); PG8_MMA(1, 1, At, B1); PG8_BAR; PG8_SCHED;
	s_add_i32 s46, 0, 0x18000
	s_add_i32 s47, 0, 0x1c000
	v_add_u32_e32 v140, s46, v198
	v_add_u32_e32 v156, s47, v198
	ds_read_b128 v[128:131], v140
	ds_read_b128 v[132:135], v140 offset:1024
	ds_read_b128 v[136:139], v140 offset:2048
	ds_read_b128 v[140:143], v140 offset:3072
	ds_read_b128 v[144:147], v156
	ds_read_b128 v[148:151], v156 offset:1024
	ds_read_b128 v[152:155], v156 offset:2048
	ds_read_b128 v[156:159], v156 offset:3072
	s_add_u32 s22, s22, 0x100000
	s_addc_u32 s23, s23, 0
	s_mov_b32 m0, s31
	ds_read_b128 v[160:163], v201 offset:32768
	ds_read_b128 v[164:167], v201 offset:33792
	ds_read_b128 v[188:191], v201 offset:34816
	ds_read_b128 v[192:195], v201 offset:35840
	ds_read_b128 v[202:205], v201 offset:36864
	ds_read_b128 v[206:209], v201 offset:37888
	ds_read_b128 v[210:213], v201 offset:38912
	ds_read_b128 v[214:217], v201 offset:39936
	global_load_lds_dwordx4 v168, s[22:23]
	s_mov_b32 m0, s33
	s_nop 0
	global_load_lds_dwordx4 v172, s[22:23]
	s_waitcnt vmcnt(8)
	s_waitcnt lgkmcnt(0)
	s_barrier
	s_setprio 1
	s_waitcnt lgkmcnt(0)
	v_mfma_f32_16x16x32_bf16 v[124:127], v[128:131], v[160:163], v[124:127]
	v_mfma_f32_16x16x32_bf16 v[120:123], v[136:139], v[160:163], v[120:123]
	v_mfma_f32_16x16x32_bf16 v[112:115], v[128:131], v[188:191], v[112:115]
	v_mfma_f32_16x16x32_bf16 v[104:107], v[136:139], v[188:191], v[104:107]
	v_mfma_f32_16x16x32_bf16 v[96:99], v[128:131], v[202:205], v[96:99]
	v_mfma_f32_16x16x32_bf16 v[88:91], v[136:139], v[202:205], v[88:91]
	v_mfma_f32_16x16x32_bf16 v[80:83], v[128:131], v[210:213], v[80:83]
	v_mfma_f32_16x16x32_bf16 v[72:75], v[136:139], v[210:213], v[72:75]
	v_mfma_f32_16x16x32_bf16 v[124:127], v[132:135], v[164:167], v[124:127]
	v_mfma_f32_16x16x32_bf16 v[120:123], v[140:143], v[164:167], v[120:123]
	v_mfma_f32_16x16x32_bf16 v[112:115], v[132:135], v[192:195], v[112:115]
	v_mfma_f32_16x16x32_bf16 v[104:107], v[140:143], v[192:195], v[104:107]
	v_mfma_f32_16x16x32_bf16 v[96:99], v[132:135], v[206:209], v[96:99]
	v_mfma_f32_16x16x32_bf16 v[88:91], v[140:143], v[206:209], v[88:91]
	v_mfma_f32_16x16x32_bf16 v[80:83], v[132:135], v[214:217], v[80:83]
	v_mfma_f32_16x16x32_bf16 v[72:75], v[140:143], v[214:217], v[72:75]
	v_mfma_f32_16x16x32_bf16 v[116:119], v[144:147], v[160:163], v[116:119]
	v_mfma_f32_16x16x32_bf16 v[108:111], v[152:155], v[160:163], v[108:111]
	v_mfma_f32_16x16x32_bf16 v[100:103], v[144:147], v[188:191], v[100:103]
	v_mfma_f32_16x16x32_bf16 v[92:95], v[152:155], v[188:191], v[92:95]
	v_mfma_f32_16x16x32_bf16 v[84:87], v[144:147], v[202:205], v[84:87]
	v_mfma_f32_16x16x32_bf16 v[76:79], v[152:155], v[202:205], v[76:79]
	v_mfma_f32_16x16x32_bf16 v[68:71], v[144:147], v[210:213], v[68:71]
	v_mfma_f32_16x16x32_bf16 v[64:67], v[152:155], v[210:213], v[64:67]
	v_mfma_f32_16x16x32_bf16 v[116:119], v[148:151], v[164:167], v[116:119]
	v_mfma_f32_16x16x32_bf16 v[108:111], v[156:159], v[164:167], v[108:111]
	v_mfma_f32_16x16x32_bf16 v[100:103], v[148:151], v[192:195], v[100:103]
	v_mfma_f32_16x16x32_bf16 v[92:95], v[156:159], v[192:195], v[92:95]
	v_mfma_f32_16x16x32_bf16 v[84:87], v[148:151], v[206:209], v[84:87]
	v_mfma_f32_16x16x32_bf16 v[76:79], v[156:159], v[206:209], v[76:79]
	v_mfma_f32_16x16x32_bf16 v[68:71], v[148:151], v[214:217], v[68:71]
	v_mfma_f32_16x16x32_bf16 v[64:67], v[156:159], v[214:217], v[64:67]
	s_setprio 0
	s_barrier
	s_add_i32 s22, s46, s29
	s_add_u32 s82, s20, s4
	s_addc_u32 s83, s21, s5
	s_mov_b32 m0, s22
	ds_read_b128 v[160:163], v201 offset:49152
	ds_read_b128 v[164:167], v201 offset:50176
	ds_read_b128 v[188:191], v201 offset:51200
	ds_read_b128 v[192:195], v201 offset:52224
	ds_read_b128 v[202:205], v201 offset:53248
	ds_read_b128 v[206:209], v201 offset:54272
	ds_read_b128 v[210:213], v201 offset:55296
	ds_read_b128 v[214:217], v201 offset:56320
	global_load_lds_dwordx4 v170, s[82:83]
	s_add_i32 m0, s22, 0x2000
	s_add_u32 s20, s20, 0x100080
	s_addc_u32 s21, s21, 0
	s_add_i32 s22, s47, s29
	global_load_lds_dwordx4 v174, s[82:83]
	s_mov_b32 m0, s22
	s_nop 0
	global_load_lds_dwordx4 v170, s[20:21]
	s_add_i32 m0, s22, 0x2000
	s_nop 0
	global_load_lds_dwordx4 v174, s[20:21]
	s_mov_b32 m0, s35
	s_nop 0
	global_load_lds_dwordx4 v168, s[80:81]
	s_mov_b32 m0, s36
	s_nop 0
	global_load_lds_dwordx4 v172, s[80:81]
	s_waitcnt vmcnt(8)
	s_waitcnt lgkmcnt(0)
	s_barrier
	s_setprio 1
	s_waitcnt lgkmcnt(0)
	v_mfma_f32_16x16x32_bf16 v[60:63], v[128:131], v[160:163], v[60:63]
	v_mfma_f32_16x16x32_bf16 v[56:59], v[136:139], v[160:163], v[56:59]
	v_mfma_f32_16x16x32_bf16 v[48:51], v[128:131], v[188:191], v[48:51]
	v_mfma_f32_16x16x32_bf16 v[40:43], v[136:139], v[188:191], v[40:43]
	v_mfma_f32_16x16x32_bf16 v[32:35], v[128:131], v[202:205], v[32:35]
	v_mfma_f32_16x16x32_bf16 v[24:27], v[136:139], v[202:205], v[24:27]
	v_mfma_f32_16x16x32_bf16 v[16:19], v[128:131], v[210:213], v[16:19]
	v_mfma_f32_16x16x32_bf16 v[8:11], v[136:139], v[210:213], v[8:11]
	v_mfma_f32_16x16x32_bf16 v[60:63], v[132:135], v[164:167], v[60:63]
	v_mfma_f32_16x16x32_bf16 v[56:59], v[140:143], v[164:167], v[56:59]
	v_mfma_f32_16x16x32_bf16 v[48:51], v[132:135], v[192:195], v[48:51]
	v_mfma_f32_16x16x32_bf16 v[40:43], v[140:143], v[192:195], v[40:43]
	v_mfma_f32_16x16x32_bf16 v[32:35], v[132:135], v[206:209], v[32:35]
	v_mfma_f32_16x16x32_bf16 v[24:27], v[140:143], v[206:209], v[24:27]
	v_mfma_f32_16x16x32_bf16 v[16:19], v[132:135], v[214:217], v[16:19]
	v_mfma_f32_16x16x32_bf16 v[8:11], v[140:143], v[214:217], v[8:11]
	v_mfma_f32_16x16x32_bf16 v[52:55], v[144:147], v[160:163], v[52:55]
	v_mfma_f32_16x16x32_bf16 v[44:47], v[152:155], v[160:163], v[44:47]
	v_mfma_f32_16x16x32_bf16 v[36:39], v[144:147], v[188:191], v[36:39]
	v_mfma_f32_16x16x32_bf16 v[28:31], v[152:155], v[188:191], v[28:31]
	v_mfma_f32_16x16x32_bf16 v[20:23], v[144:147], v[202:205], v[20:23]
	v_mfma_f32_16x16x32_bf16 v[12:15], v[152:155], v[202:205], v[12:15]
	v_mfma_f32_16x16x32_bf16 v[4:7], v[144:147], v[210:213], v[4:7]
	v_mfma_f32_16x16x32_bf16 v[0:3], v[152:155], v[210:213], v[0:3]
	v_mfma_f32_16x16x32_bf16 v[52:55], v[148:151], v[164:167], v[52:55]
	v_mfma_f32_16x16x32_bf16 v[44:47], v[156:159], v[164:167], v[44:47]
	v_mfma_f32_16x16x32_bf16 v[36:39], v[148:151], v[192:195], v[36:39]
	v_mfma_f32_16x16x32_bf16 v[28:31], v[156:159], v[192:195], v[28:31]
	v_mfma_f32_16x16x32_bf16 v[20:23], v[148:151], v[206:209], v[20:23]
	v_mfma_f32_16x16x32_bf16 v[12:15], v[156:159], v[206:209], v[12:15]
	v_mfma_f32_16x16x32_bf16 v[4:7], v[148:151], v[214:217], v[4:7]
	v_mfma_f32_16x16x32_bf16 v[0:3], v[156:159], v[214:217], v[0:3]
	s_setprio 0
	s_barrier
	s_add_i32 s45, s45, 2
	s_add_u32 s18, s18, 0x100
	s_addc_u32 s19, s19, 0
	s_add_u32 s43, s43, 0x100
	s_addc_u32 s44, s44, 0
	s_cmp_gt_u32 s45, 61
	s_cbranch_scc0 .LBB0_1061
	s_and_b64 vcc, exec, s[6:7]
	s_cbranch_vccz .LBB0_1064
	s_barrier
